# E4/O5 big-tile epilogue: pairs of 8-byte row stores merged into 16-byte stores via v_permlane16_swap (half the store instructions)
# speedup vs baseline: 1.0124x; 1.0066x over previous
; template <int N> DI void wait_vm() { asm volatile("s_waitcnt vmcnt(%0)" ::"n"(N) : "memory"); }
; template <int BM, class Epi>
; DI void gemm_dma(const u16* __restrict__ X, long ldx, const u16* __restrict__ W, long ldw, int K, char* smem,
;                  int m0, int n0, const Epi& epi) {
;     ...
;   do {
;     if (kt + D - 2 < nk) wait_vm<PW * (D - 2)>(); else wait_vm<0>();
;     __syncthreads();
;     if (kt + D - 1 < nk) GD_ISSUE(nxt)
;     nxt = (nxt + 1 == D) ? 0 : nxt + 1;
;     const char* base = smem + cur * STG;
;     cur = (cur + 1 == D) ? 0 : cur + 1;
;     bf16x8 xf[MT];
; #pragma unroll
;     for (int i = 0; i < MT; ++i) xf[i] = *(const bf16x8*)(base + (xrow0 + i * 16) * 64 + rd);
; #pragma unroll
;     for (int nh = 0; nh < NT / 4; ++nh) {
;       bf16x8 wf[4];
; #pragma unroll
;       for (int i = 0; i < 4; ++i) wf[i] = *(const bf16x8*)(base + BM * 64 + (wrow0 + (nh * 4 + i) * 16) * 64 + rd);
; #pragma unroll
;       for (int i = 0; i < 4; ++i)
; #pragma unroll
;         for (int mt = 0; mt < MT; ++mt)
;           acc[nh * 4 + i][mt] = __builtin_amdgcn_mfma_f32_16x16x32_bf16(wf[i], xf[mt], acc[nh * 4 + i][mt], 0, 0, 0);
;     }
;   } while (++kt < nk);
;     ...
;   epi.run(acc, m0 + xrow0 + lr, n0 + wrow0 + 4 * g);
.LBB0_32:
	s_mul_i32 s12, s10, 0x6000
	v_lshl_add_u64 v[196:197], v[130:131], 0, s[40:41]
	s_waitcnt vmcnt(6)
	s_barrier
	s_mul_i32 s98, s11, 0x6000
	v_or_b32_e32 v137, s98, v134
	v_add_u32_e32 v150, v137, v136
	ds_read_b128 v[138:141], v150
	ds_read_b128 v[142:145], v150 offset:1024
	ds_read_b128 v[146:149], v150 offset:2048
	ds_read_b128 v[150:153], v150 offset:3072
	ds_read_b128 v[154:157], v137 offset:16384
	ds_read_b128 v[158:161], v137 offset:17408
	ds_read_b128 v[162:165], v137 offset:18432
	ds_read_b128 v[166:169], v137 offset:19456
	ds_read_b128 v[226:229], v137 offset:20480
	ds_read_b128 v[230:233], v137 offset:21504
	ds_read_b128 v[234:237], v137 offset:22528
	ds_read_b128 v[238:241], v137 offset:23552
	s_add_i32 s13, s12, s8
	s_mov_b32 m0, s13
	s_nop 0
	global_load_lds_dwordx4 v[196:197], off
	v_lshl_add_u64 v[224:225], v[196:197], 0, s[16:17]
	s_add_i32 s14, s13, 0x400
	s_mov_b32 m0, s14
	s_nop 0
	global_load_lds_dwordx4 v[224:225], off
	v_lshl_add_u64 v[224:225], v[196:197], 0, s[18:19]
	s_add_i32 s14, s13, 0x800
	s_mov_b32 m0, s14
	s_nop 0
	global_load_lds_dwordx4 v[224:225], off
	v_lshl_add_u64 v[196:197], v[196:197], 0, s[20:21]
	s_addk_i32 s13, 0xc00
	s_mov_b32 m0, s13
	s_nop 0
	global_load_lds_dwordx4 v[196:197], off
	s_add_i32 s12, s12, s9
	v_lshl_add_u64 v[194:195], v[128:129], 0, s[40:41]
	s_mov_b32 m0, s12
	s_nop 0
	global_load_lds_dwordx4 v[194:195], off
	s_addk_i32 s12, 0x400
	v_lshl_add_u64 v[194:195], v[194:195], 0, s[16:17]
	s_mov_b32 m0, s12
	s_nop 0
	global_load_lds_dwordx4 v[194:195], off
	s_waitcnt lgkmcnt(7)
	v_mfma_f32_16x16x32_bf16 v[124:127], v[154:157], v[138:141], v[124:127]
	s_add_i32 s10, s10, 1
	s_add_i32 s11, s11, 1
	s_cmp_lg_u32 s10, 3
	v_mfma_f32_16x16x32_bf16 v[120:123], v[154:157], v[142:145], v[120:123]
	s_cselect_b32 s10, s10, 0
	s_cmp_lg_u32 s11, 3
	s_cselect_b32 s11, s11, 0
	v_mfma_f32_16x16x32_bf16 v[116:119], v[154:157], v[146:149], v[116:119]
	s_add_u32 s40, s40, 64
	s_addc_u32 s41, s41, 0
	s_cmpk_lg_i32 s40, 0x780
	v_mfma_f32_16x16x32_bf16 v[112:115], v[154:157], v[150:153], v[112:115]
	s_waitcnt lgkmcnt(6)
	v_mfma_f32_16x16x32_bf16 v[108:111], v[158:161], v[138:141], v[108:111]
	v_mfma_f32_16x16x32_bf16 v[104:107], v[158:161], v[142:145], v[104:107]
	v_mfma_f32_16x16x32_bf16 v[100:103], v[158:161], v[146:149], v[100:103]
	v_mfma_f32_16x16x32_bf16 v[96:99], v[158:161], v[150:153], v[96:99]
	s_waitcnt lgkmcnt(5)
	v_mfma_f32_16x16x32_bf16 v[92:95], v[162:165], v[138:141], v[92:95]
	v_mfma_f32_16x16x32_bf16 v[88:91], v[162:165], v[142:145], v[88:91]
	v_mfma_f32_16x16x32_bf16 v[84:87], v[162:165], v[146:149], v[84:87]
	v_mfma_f32_16x16x32_bf16 v[80:83], v[162:165], v[150:153], v[80:83]
	s_waitcnt lgkmcnt(4)
	v_mfma_f32_16x16x32_bf16 v[76:79], v[166:169], v[138:141], v[76:79]
	v_mfma_f32_16x16x32_bf16 v[72:75], v[166:169], v[142:145], v[72:75]
	v_mfma_f32_16x16x32_bf16 v[68:71], v[166:169], v[146:149], v[68:71]
	v_mfma_f32_16x16x32_bf16 v[64:67], v[166:169], v[150:153], v[64:67]
	s_waitcnt lgkmcnt(3)
	v_mfma_f32_16x16x32_bf16 v[60:63], v[226:229], v[138:141], v[60:63]
	v_mfma_f32_16x16x32_bf16 v[56:59], v[226:229], v[142:145], v[56:59]
	v_mfma_f32_16x16x32_bf16 v[52:55], v[226:229], v[146:149], v[52:55]
	v_mfma_f32_16x16x32_bf16 v[48:51], v[226:229], v[150:153], v[48:51]
	s_waitcnt lgkmcnt(2)
	v_mfma_f32_16x16x32_bf16 v[44:47], v[230:233], v[138:141], v[44:47]
	v_mfma_f32_16x16x32_bf16 v[40:43], v[230:233], v[142:145], v[40:43]
	v_mfma_f32_16x16x32_bf16 v[36:39], v[230:233], v[146:149], v[36:39]
	v_mfma_f32_16x16x32_bf16 v[32:35], v[230:233], v[150:153], v[32:35]
	s_waitcnt lgkmcnt(1)
	v_mfma_f32_16x16x32_bf16 v[28:31], v[234:237], v[138:141], v[28:31]
	v_mfma_f32_16x16x32_bf16 v[24:27], v[234:237], v[142:145], v[24:27]
	v_mfma_f32_16x16x32_bf16 v[20:23], v[234:237], v[146:149], v[20:23]
	v_mfma_f32_16x16x32_bf16 v[16:19], v[234:237], v[150:153], v[16:19]
	s_waitcnt lgkmcnt(0)
	v_mfma_f32_16x16x32_bf16 v[12:15], v[238:241], v[138:141], v[12:15]
	v_mfma_f32_16x16x32_bf16 v[8:11], v[238:241], v[142:145], v[8:11]
	v_mfma_f32_16x16x32_bf16 v[4:7], v[238:241], v[146:149], v[4:7]
	v_mfma_f32_16x16x32_bf16 v[0:3], v[238:241], v[150:153], v[0:3]
	s_cbranch_scc1 .LBB0_32
	v_add_u32_e32 v180, v134, v136
	s_waitcnt vmcnt(6)
	s_barrier
	ds_read_b128 v[128:131], v180
	ds_read_b128 v[136:139], v180 offset:1024
	ds_read_b128 v[140:143], v180 offset:2048
	ds_read_b128 v[144:147], v180 offset:3072
	ds_read_b128 v[148:151], v134 offset:16384
	ds_read_b128 v[152:155], v134 offset:17408
	ds_read_b128 v[156:159], v134 offset:18432
	ds_read_b128 v[160:163], v134 offset:19456
	s_waitcnt lgkmcnt(3)
	v_mfma_f32_16x16x32_bf16 v[124:127], v[148:151], v[128:131], v[124:127]
	s_lshl_b32 s7, s7, 8
	v_lshl_or_b32 v182, v132, 3, s7
	v_and_b32_e32 v251, 1, v132
	v_mad_u32_u24 v182, v251, 24, v182
	v_mfma_f32_16x16x32_bf16 v[120:123], v[148:151], v[136:139], v[120:123]
	v_mfma_f32_16x16x32_bf16 v[116:119], v[148:151], v[140:143], v[116:119]
	v_mfma_f32_16x16x32_bf16 v[112:115], v[148:151], v[144:147], v[112:115]
	s_waitcnt lgkmcnt(2)
	v_mfma_f32_16x16x32_bf16 v[108:111], v[152:155], v[128:131], v[108:111]
	v_mfma_f32_16x16x32_bf16 v[104:107], v[152:155], v[136:139], v[104:107]
	v_mfma_f32_16x16x32_bf16 v[100:103], v[152:155], v[140:143], v[100:103]
	v_mfma_f32_16x16x32_bf16 v[96:99], v[152:155], v[144:147], v[96:99]
	s_waitcnt lgkmcnt(1)
	v_mfma_f32_16x16x32_bf16 v[92:95], v[156:159], v[128:131], v[92:95]
	v_mfma_f32_16x16x32_bf16 v[88:91], v[156:159], v[136:139], v[88:91]
	v_mfma_f32_16x16x32_bf16 v[84:87], v[156:159], v[140:143], v[84:87]
	v_mfma_f32_16x16x32_bf16 v[148:151], v[156:159], v[144:147], v[80:83]
	s_waitcnt lgkmcnt(0)
	v_mfma_f32_16x16x32_bf16 v[76:79], v[160:163], v[128:131], v[76:79]
	v_mfma_f32_16x16x32_bf16 v[152:155], v[160:163], v[136:139], v[72:75]
	v_mfma_f32_16x16x32_bf16 v[68:71], v[160:163], v[140:143], v[68:71]
	v_mfma_f32_16x16x32_bf16 v[156:159], v[160:163], v[144:147], v[64:67]
	s_nop 2
	ds_read_b128 v[64:67], v134 offset:20480
	ds_read_b128 v[72:75], v134 offset:21504
	ds_read_b128 v[80:83], v134 offset:22528
	ds_read_b128 v[160:163], v134 offset:23552
	s_waitcnt vmcnt(0)
	s_waitcnt lgkmcnt(0)
	v_mfma_f32_16x16x32_bf16 v[60:63], v[64:67], v[128:131], v[60:63]
	s_barrier
; template <int BM, class Epi>
; DI void gemm_dma(const u16* __restrict__ X, long ldx, const u16* __restrict__ W, long ldw, int K, char* smem,
;                  int m0, int n0, const Epi& epi) {
;     ...
;     bf16x8 xf[MT];
; #pragma unroll
;     for (int i = 0; i < MT; ++i) xf[i] = *(const bf16x8*)(base + (xrow0 + i * 16) * 64 + rd);
; #pragma unroll
;     for (int nh = 0; nh < NT / 4; ++nh) {
;       bf16x8 wf[4];
; #pragma unroll
;       for (int i = 0; i < 4; ++i) wf[i] = *(const bf16x8*)(base + BM * 64 + (wrow0 + (nh * 4 + i) * 16) * 64 + rd);
; #pragma unroll
;       for (int i = 0; i < 4; ++i)
; #pragma unroll
;         for (int mt = 0; mt < MT; ++mt)
;           acc[nh * 4 + i][mt] = __builtin_amdgcn_mfma_f32_16x16x32_bf16(wf[i], xf[mt], acc[nh * 4 + i][mt], 0, 0, 0);
;     }
	v_mfma_f32_16x16x32_bf16 v[164:167], v[64:67], v[136:139], v[56:59]
	v_mfma_f32_16x16x32_bf16 v[52:55], v[64:67], v[140:143], v[52:55]
	v_mfma_f32_16x16x32_bf16 v[168:171], v[64:67], v[144:147], v[48:51]
	v_mfma_f32_16x16x32_bf16 v[44:47], v[72:75], v[128:131], v[44:47]
	v_mfma_f32_16x16x32_bf16 v[172:175], v[72:75], v[136:139], v[40:43]
	v_mfma_f32_16x16x32_bf16 v[36:39], v[72:75], v[140:143], v[36:39]
	v_mfma_f32_16x16x32_bf16 v[176:179], v[72:75], v[144:147], v[32:35]
	v_mfma_f32_16x16x32_bf16 v[28:31], v[80:83], v[128:131], v[28:31]
	v_mfma_f32_16x16x32_bf16 v[24:27], v[80:83], v[136:139], v[24:27]
	v_mfma_f32_16x16x32_bf16 v[20:23], v[80:83], v[140:143], v[20:23]
	v_mfma_f32_16x16x32_bf16 v[16:19], v[80:83], v[144:147], v[16:19]
	v_mfma_f32_16x16x32_bf16 v[12:15], v[160:163], v[128:131], v[12:15]
	v_mfma_f32_16x16x32_bf16 v[8:11], v[160:163], v[136:139], v[8:11]
	v_mfma_f32_16x16x32_bf16 v[4:7], v[160:163], v[140:143], v[4:7]
	v_mfma_f32_16x16x32_bf16 v[0:3], v[160:163], v[144:147], v[0:3]
	ds_read_b128 v[128:131], v180 offset:24576
	ds_read_b128 v[136:139], v180 offset:25600
	ds_read_b128 v[140:143], v180 offset:26624
	ds_read_b128 v[144:147], v180 offset:27648
	ds_read_b128 v[32:35], v134 offset:40960
	ds_read_b128 v[40:43], v134 offset:41984
	ds_read_b128 v[48:51], v134 offset:43008
	ds_read_b128 v[160:163], v134 offset:44032
	s_waitcnt lgkmcnt(2)
	v_mfma_f32_16x16x32_bf16 v[108:111], v[40:43], v[128:131], v[108:111]
	v_mfma_f32_16x16x32_bf16 v[104:107], v[40:43], v[136:139], v[104:107]
	v_mfma_f32_16x16x32_bf16 v[100:103], v[40:43], v[140:143], v[100:103]
	s_nop 5
	v_cvt_pk_bf16_f32 v108, v108, v109
	v_cvt_pk_bf16_f32 v109, v110, v111
	v_cvt_pk_bf16_f32 v104, v104, v105
	v_mfma_f32_16x16x32_bf16 v[96:99], v[40:43], v[144:147], v[96:99]
	v_cvt_pk_bf16_f32 v105, v106, v107
	v_cvt_pk_bf16_f32 v100, v100, v101
	v_cvt_pk_bf16_f32 v101, v102, v103
	s_waitcnt lgkmcnt(1)
	v_mfma_f32_16x16x32_bf16 v[92:95], v[48:51], v[128:131], v[92:95]
	v_mfma_f32_16x16x32_bf16 v[80:83], v[48:51], v[136:139], v[88:91]
	s_nop 1
	v_cvt_pk_bf16_f32 v96, v96, v97
	v_cvt_pk_bf16_f32 v97, v98, v99
	s_nop 2
	v_cvt_pk_bf16_f32 v92, v92, v93
	v_mfma_f32_16x16x32_bf16 v[72:75], v[48:51], v[140:143], v[84:87]
	v_cvt_pk_bf16_f32 v93, v94, v95
	v_cvt_pk_bf16_f32 v80, v80, v81
	v_cvt_pk_bf16_f32 v81, v82, v83
	v_mfma_f32_16x16x32_bf16 v[64:67], v[48:51], v[144:147], v[148:151]
	s_waitcnt lgkmcnt(0)
	v_mfma_f32_16x16x32_bf16 v[48:51], v[160:163], v[136:139], v[152:155]
	s_nop 1
	v_cvt_pk_bf16_f32 v72, v72, v73
	v_cvt_pk_bf16_f32 v73, v74, v75
	s_nop 1
	v_cvt_pk_bf16_f32 v64, v64, v65
	v_mfma_f32_16x16x32_bf16 v[40:43], v[160:163], v[140:143], v[68:71]
	s_nop 2
	ds_read_b128 v[68:71], v134 offset:45056
	ds_read_b128 v[88:91], v134 offset:46080
	ds_read_b128 v[148:151], v134 offset:47104
	ds_read_b128 v[152:155], v134 offset:48128
	v_cvt_pk_bf16_f32 v65, v66, v67
	v_cvt_pk_bf16_f32 v48, v48, v49
	v_mfma_f32_16x16x32_bf16 v[124:127], v[32:35], v[128:131], v[124:127]
	v_cvt_pk_bf16_f32 v49, v50, v51
	v_cvt_pk_bf16_f32 v40, v40, v41
	v_cvt_pk_bf16_f32 v41, v42, v43
	v_mfma_f32_16x16x32_bf16 v[120:123], v[32:35], v[136:139], v[120:123]
	v_mfma_f32_16x16x32_bf16 v[116:119], v[32:35], v[140:143], v[116:119]
	v_mfma_f32_16x16x32_bf16 v[112:115], v[32:35], v[144:147], v[112:115]
	s_nop 5
	v_cvt_pk_bf16_f32 v120, v120, v121
	v_cvt_pk_bf16_f32 v121, v122, v123
	v_cvt_pk_bf16_f32 v116, v116, v117
	v_mfma_f32_16x16x32_bf16 v[56:59], v[160:163], v[128:131], v[76:79]
	v_cvt_pk_bf16_f32 v117, v118, v119
	v_cvt_pk_bf16_f32 v112, v112, v113
	v_cvt_pk_bf16_f32 v113, v114, v115
	v_mfma_f32_16x16x32_bf16 v[32:35], v[160:163], v[144:147], v[156:159]
	s_waitcnt lgkmcnt(3)
	v_mfma_f32_16x16x32_bf16 v[156:159], v[68:71], v[128:131], v[60:63]
	s_nop 1
	v_cvt_pk_bf16_f32 v56, v56, v57
	s_nop 2
	v_cvt_pk_bf16_f32 v32, v32, v33
	v_cvt_pk_bf16_f32 v33, v34, v35
	v_mfma_f32_16x16x32_bf16 v[76:79], v[68:71], v[140:143], v[52:55]
	v_cvt_pk_bf16_f32 v57, v58, v59
	s_waitcnt lgkmcnt(2)
	v_mfma_f32_16x16x32_bf16 v[60:63], v[88:91], v[128:131], v[44:47]
	v_mfma_f32_16x16x32_bf16 v[52:55], v[88:91], v[136:139], v[172:175]
	v_mfma_f32_16x16x32_bf16 v[44:47], v[88:91], v[140:143], v[36:39]
	v_mfma_f32_16x16x32_bf16 v[36:39], v[88:91], v[144:147], v[176:179]
	v_lshl_add_u32 v88, s38, 8, v135
	v_cvt_pk_bf16_f32 v90, v124, v125
	v_cvt_pk_bf16_f32 v91, v126, v127
	s_waitcnt lgkmcnt(1)
	v_mfma_f32_16x16x32_bf16 v[28:31], v[148:151], v[128:131], v[28:31]
	s_waitcnt lgkmcnt(0)
; DI void st_bf4(u16* p, float a, float b, float c, float d) { *(uint2*)p = make_uint2(pk2(a, b), pk2(c, d)); }
;   template <int NT, int MT> DI void run(f32x4 (&acc)[NT][MT], int mb, int nb) const {
; #pragma unroll
;     for (int nt = 0; nt < NT; ++nt)
; #pragma unroll
;       for (int mt = 0; mt < MT; ++mt) {
;         f32x4 v = acc[nt][mt];
;         st_bf4(C + (size_t)(mb + mt * 16) * ldc + nb + nt * 16, v[0], v[1], v[2], v[3]);
;       }
;   }
	v_mfma_f32_16x16x32_bf16 v[12:15], v[152:155], v[128:131], v[12:15]
	v_or_b32_e32 v128, v88, v133
	v_ashrrev_i32_e32 v129, 31, v128
	v_lshlrev_b64 v[88:89], 11, v[128:129]
	v_lshl_add_u64 v[88:89], s[92:93], 0, v[88:89]
	v_lshl_add_u64 v[88:89], v[88:89], 0, v[182:183]
	v_mov_b32_e32 v194, v90
	v_mov_b32_e32 v195, v91
	v_or_b32_e32 v90, 16, v128
	v_ashrrev_i32_e32 v91, 31, v90
	v_lshlrev_b64 v[90:91], 11, v[90:91]
	v_lshl_add_u64 v[90:91], s[92:93], 0, v[90:91]
	v_lshl_add_u64 v[90:91], v[90:91], 0, v[182:183]
	v_mov_b32_e32 v224, v120
	v_mov_b32_e32 v225, v121
	v_or_b32_e32 v120, 32, v128
	v_ashrrev_i32_e32 v121, 31, v120
	v_lshlrev_b64 v[120:121], 11, v[120:121]
	v_lshl_add_u64 v[120:121], s[92:93], 0, v[120:121]
	v_lshl_add_u64 v[120:121], v[120:121], 0, v[182:183]
	v_mov_b32_e32 v228, v116
	v_mov_b32_e32 v229, v117
	v_or_b32_e32 v116, 48, v128
	v_ashrrev_i32_e32 v117, 31, v116
	v_mfma_f32_16x16x32_bf16 v[84:87], v[68:71], v[136:139], v[164:167]
	v_lshlrev_b64 v[116:117], 11, v[116:117]
	v_lshl_add_u64 v[116:117], s[92:93], 0, v[116:117]
	v_lshl_add_u64 v[116:117], v[116:117], 0, v[182:183]
	v_mfma_f32_16x16x32_bf16 v[68:71], v[68:71], v[144:147], v[168:171]
	v_mov_b32_e32 v234, v32
	v_mov_b32_e32 v235, v33
	v_cvt_pk_bf16_f32 v32, v156, v157
	v_cvt_pk_bf16_f32 v33, v158, v159
	v_mov_b32_e32 v236, v32
	v_mov_b32_e32 v237, v33
	v_cvt_pk_bf16_f32 v32, v84, v85
	v_cvt_pk_bf16_f32 v33, v86, v87
	v_mov_b32_e32 v240, v32
	v_mov_b32_e32 v241, v33
	v_cvt_pk_bf16_f32 v32, v76, v77
	v_cvt_pk_bf16_f32 v33, v78, v79
	v_mfma_f32_16x16x32_bf16 v[24:27], v[148:151], v[136:139], v[24:27]
	v_mov_b32_e32 v244, v32
	v_mov_b32_e32 v245, v33
	v_cvt_pk_bf16_f32 v32, v68, v69
	v_cvt_pk_bf16_f32 v33, v70, v71
	v_mfma_f32_16x16x32_bf16 v[20:23], v[148:151], v[140:143], v[20:23]
	v_mov_b32_e32 v248, v32
	v_mov_b32_e32 v249, v33
	v_cvt_pk_bf16_f32 v32, v60, v61
	v_cvt_pk_bf16_f32 v33, v62, v63
	v_mfma_f32_16x16x32_bf16 v[16:19], v[148:151], v[144:147], v[16:19]
	v_mov_b32_e32 v238, v32
	v_mov_b32_e32 v239, v33
	s_nop 1
	v_permlane16_swap_b32_e32 v236, v238
	v_permlane16_swap_b32_e32 v237, v239
	global_store_dwordx4 v[88:89], v[236:239], off offset:128
	v_cvt_pk_bf16_f32 v32, v52, v53
	v_cvt_pk_bf16_f32 v33, v54, v55
	v_mfma_f32_16x16x32_bf16 v[8:11], v[152:155], v[136:139], v[8:11]
	v_mov_b32_e32 v242, v32
	v_mov_b32_e32 v243, v33
	s_nop 1
	v_permlane16_swap_b32_e32 v240, v242
	v_permlane16_swap_b32_e32 v241, v243
	global_store_dwordx4 v[90:91], v[240:243], off offset:128
	v_cvt_pk_bf16_f32 v32, v44, v45
	v_cvt_pk_bf16_f32 v33, v46, v47
	v_mfma_f32_16x16x32_bf16 v[4:7], v[152:155], v[140:143], v[4:7]
	v_mov_b32_e32 v246, v32
	v_mov_b32_e32 v247, v33
	s_nop 1
	v_permlane16_swap_b32_e32 v244, v246
	v_permlane16_swap_b32_e32 v245, v247
	global_store_dwordx4 v[120:121], v[244:247], off offset:128
	v_cvt_pk_bf16_f32 v32, v36, v37
	v_cvt_pk_bf16_f32 v33, v38, v39
	v_mfma_f32_16x16x32_bf16 v[0:3], v[152:155], v[144:147], v[0:3]
	v_cvt_pk_bf16_f32 v28, v28, v29
	v_cvt_pk_bf16_f32 v29, v30, v31
	v_cvt_pk_bf16_f32 v24, v24, v25
	v_cvt_pk_bf16_f32 v25, v26, v27
	v_cvt_pk_bf16_f32 v20, v20, v21
	v_cvt_pk_bf16_f32 v21, v22, v23
	v_cvt_pk_bf16_f32 v16, v16, v17
	v_cvt_pk_bf16_f32 v17, v18, v19
	v_cvt_pk_bf16_f32 v12, v12, v13
	v_cvt_pk_bf16_f32 v13, v14, v15
	v_cvt_pk_bf16_f32 v8, v8, v9
	v_cvt_pk_bf16_f32 v9, v10, v11
	v_cvt_pk_bf16_f32 v4, v4, v5
	v_cvt_pk_bf16_f32 v5, v6, v7
	v_cvt_pk_bf16_f32 v0, v0, v1
	v_cvt_pk_bf16_f32 v1, v2, v3
	v_mov_b32_e32 v66, v112
	v_mov_b32_e32 v67, v113
	v_mov_b32_e32 v196, v108
	v_mov_b32_e32 v197, v109
	s_nop 1
	v_permlane16_swap_b32_e32 v194, v196
	v_permlane16_swap_b32_e32 v195, v197
	global_store_dwordx4 v[88:89], v[194:197], off
	v_mov_b32_e32 v226, v104
	v_mov_b32_e32 v227, v105
	s_nop 1
	v_permlane16_swap_b32_e32 v224, v226
	v_permlane16_swap_b32_e32 v225, v227
	global_store_dwordx4 v[90:91], v[224:227], off
	v_mov_b32_e32 v230, v100
	v_mov_b32_e32 v231, v101
	s_nop 1
	v_permlane16_swap_b32_e32 v228, v230
	v_permlane16_swap_b32_e32 v229, v231
	global_store_dwordx4 v[120:121], v[228:231], off
	v_mov_b32_e32 v68, v96
	v_mov_b32_e32 v69, v97
	s_nop 1
	v_permlane16_swap_b32_e32 v66, v68
	v_permlane16_swap_b32_e32 v67, v69
	global_store_dwordx4 v[116:117], v[66:69], off
	v_mov_b32_e32 v128, v92
	v_mov_b32_e32 v129, v93
	v_mov_b32_e32 v136, v80
	v_mov_b32_e32 v137, v81
	v_mov_b32_e32 v140, v72
	v_mov_b32_e32 v141, v73
	v_mov_b32_e32 v232, v64
	v_mov_b32_e32 v233, v65
	s_nop 1
	v_permlane16_swap_b32_e32 v232, v234
	v_permlane16_swap_b32_e32 v233, v235
	global_store_dwordx4 v[116:117], v[232:235], off offset:64
	v_mov_b32_e32 v130, v56
	v_mov_b32_e32 v131, v57
	s_nop 1
	v_permlane16_swap_b32_e32 v128, v130
	v_permlane16_swap_b32_e32 v129, v131
	global_store_dwordx4 v[88:89], v[128:131], off offset:64
	v_mov_b32_e32 v138, v48
	v_mov_b32_e32 v139, v49
	s_nop 1
	v_permlane16_swap_b32_e32 v136, v138
	v_permlane16_swap_b32_e32 v137, v139
	global_store_dwordx4 v[90:91], v[136:139], off offset:64
	v_mov_b32_e32 v142, v40
	v_mov_b32_e32 v143, v41
	s_nop 1
	v_permlane16_swap_b32_e32 v140, v142
	v_permlane16_swap_b32_e32 v141, v143
	global_store_dwordx4 v[120:121], v[140:143], off offset:64
	v_mov_b32_e32 v250, v32
	v_mov_b32_e32 v251, v33
	s_nop 1
	v_permlane16_swap_b32_e32 v248, v250
	v_permlane16_swap_b32_e32 v249, v251
	global_store_dwordx4 v[116:117], v[248:251], off offset:128
	v_mov_b32_e32 v66, v28
	v_mov_b32_e32 v67, v29
	v_mov_b32_e32 v128, v24
	v_mov_b32_e32 v129, v25
	v_mov_b32_e32 v136, v20
	v_mov_b32_e32 v137, v21
	v_mov_b32_e32 v140, v16
	v_mov_b32_e32 v141, v17
	v_mov_b32_e32 v68, v12
	v_mov_b32_e32 v69, v13
	s_nop 1
	v_permlane16_swap_b32_e32 v66, v68
	v_permlane16_swap_b32_e32 v67, v69
	global_store_dwordx4 v[88:89], v[66:69], off offset:192
	v_mov_b32_e32 v130, v8
	v_mov_b32_e32 v131, v9
	s_nop 1
	v_permlane16_swap_b32_e32 v128, v130
	v_permlane16_swap_b32_e32 v129, v131
	global_store_dwordx4 v[90:91], v[128:131], off offset:192
	v_mov_b32_e32 v138, v4
	v_mov_b32_e32 v139, v5
	s_nop 1
	v_permlane16_swap_b32_e32 v136, v138
	v_permlane16_swap_b32_e32 v137, v139
	global_store_dwordx4 v[120:121], v[136:139], off offset:192
	v_mov_b32_e32 v142, v0
	v_mov_b32_e32 v143, v1
	s_nop 1
	v_permlane16_swap_b32_e32 v140, v142
	v_permlane16_swap_b32_e32 v141, v143
	global_store_dwordx4 v[116:117], v[140:143], off offset:192
	s_branch .LBB0_25

; template <int N> DI void wait_vm() { asm volatile("s_waitcnt vmcnt(%0)" ::"n"(N) : "memory"); }
; template <int BM, class Epi>
; DI void gemm_dma(const u16* __restrict__ X, long ldx, const u16* __restrict__ W, long ldw, int K, char* smem,
;                  int m0, int n0, const Epi& epi) {
;     ...
;   do {
;     if (kt + D - 2 < nk) wait_vm<PW * (D - 2)>(); else wait_vm<0>();
;     __syncthreads();
;     if (kt + D - 1 < nk) GD_ISSUE(nxt)
;     nxt = (nxt + 1 == D) ? 0 : nxt + 1;
;     const char* base = smem + cur * STG;
;     cur = (cur + 1 == D) ? 0 : cur + 1;
;     bf16x8 xf[MT];
; #pragma unroll
;     for (int i = 0; i < MT; ++i) xf[i] = *(const bf16x8*)(base + (xrow0 + i * 16) * 64 + rd);
; #pragma unroll
;     for (int nh = 0; nh < NT / 4; ++nh) {
;       bf16x8 wf[4];
; #pragma unroll
;       for (int i = 0; i < 4; ++i) wf[i] = *(const bf16x8*)(base + BM * 64 + (wrow0 + (nh * 4 + i) * 16) * 64 + rd);
; #pragma unroll
;       for (int i = 0; i < 4; ++i)
; #pragma unroll
;         for (int mt = 0; mt < MT; ++mt)
;           acc[nh * 4 + i][mt] = __builtin_amdgcn_mfma_f32_16x16x32_bf16(wf[i], xf[mt], acc[nh * 4 + i][mt], 0, 0, 0);
;     }
;   } while (++kt < nk);
;     ...
;   epi.run(acc, m0 + xrow0 + lr, n0 + wrow0 + 4 * g);
.LBB0_292:
	s_mul_i32 s12, s10, 0x6000
	v_lshl_add_u64 v[196:197], v[132:133], 0, s[40:41]
	s_waitcnt vmcnt(6)
	s_barrier
	s_mul_i32 s98, s11, 0x6000
	v_or_b32_e32 v170, s98, v135
	v_add_u32_e32 v150, v170, v137
	ds_read_b128 v[138:141], v150
	ds_read_b128 v[142:145], v150 offset:1024
	ds_read_b128 v[146:149], v150 offset:2048
	ds_read_b128 v[150:153], v150 offset:3072
	ds_read_b128 v[154:157], v170 offset:16384
	ds_read_b128 v[158:161], v170 offset:17408
	ds_read_b128 v[162:165], v170 offset:18432
	ds_read_b128 v[166:169], v170 offset:19456
	ds_read_b128 v[226:229], v170 offset:20480
	ds_read_b128 v[230:233], v170 offset:21504
	ds_read_b128 v[234:237], v170 offset:22528
	ds_read_b128 v[238:241], v170 offset:23552
	s_add_i32 s13, s12, s8
	s_mov_b32 m0, s13
	s_nop 0
	global_load_lds_dwordx4 v[196:197], off
	v_lshl_add_u64 v[224:225], v[196:197], 0, s[16:17]
	s_add_i32 s14, s13, 0x400
	s_mov_b32 m0, s14
	s_nop 0
	global_load_lds_dwordx4 v[224:225], off
	v_lshl_add_u64 v[224:225], v[196:197], 0, s[20:21]
	s_add_i32 s14, s13, 0x800
	s_mov_b32 m0, s14
	s_nop 0
	global_load_lds_dwordx4 v[224:225], off
	v_lshl_add_u64 v[196:197], v[196:197], 0, s[22:23]
	s_addk_i32 s13, 0xc00
	s_mov_b32 m0, s13
	s_nop 0
	global_load_lds_dwordx4 v[196:197], off
	s_add_i32 s12, s12, s9
	v_lshl_add_u64 v[194:195], v[130:131], 0, s[40:41]
	s_mov_b32 m0, s12
	s_nop 0
	global_load_lds_dwordx4 v[194:195], off
	s_addk_i32 s12, 0x400
	v_lshl_add_u64 v[194:195], v[194:195], 0, s[16:17]
	s_mov_b32 m0, s12
	s_nop 0
	global_load_lds_dwordx4 v[194:195], off
	s_waitcnt lgkmcnt(7)
	v_mfma_f32_16x16x32_bf16 v[126:129], v[154:157], v[138:141], v[126:129]
	s_add_i32 s10, s10, 1
	s_add_i32 s11, s11, 1
	s_cmp_lg_u32 s10, 3
	v_mfma_f32_16x16x32_bf16 v[122:125], v[154:157], v[142:145], v[122:125]
	s_cselect_b32 s10, s10, 0
	s_cmp_lg_u32 s11, 3
	s_cselect_b32 s11, s11, 0
	v_mfma_f32_16x16x32_bf16 v[118:121], v[154:157], v[146:149], v[118:121]
	s_add_u32 s40, s40, 64
	s_addc_u32 s41, s41, 0
	s_cmpk_lg_i32 s40, 0xf80
	v_mfma_f32_16x16x32_bf16 v[114:117], v[154:157], v[150:153], v[114:117]
	s_waitcnt lgkmcnt(6)
	v_mfma_f32_16x16x32_bf16 v[110:113], v[158:161], v[138:141], v[110:113]
	v_mfma_f32_16x16x32_bf16 v[106:109], v[158:161], v[142:145], v[106:109]
	v_mfma_f32_16x16x32_bf16 v[102:105], v[158:161], v[146:149], v[102:105]
	v_mfma_f32_16x16x32_bf16 v[98:101], v[158:161], v[150:153], v[98:101]
	s_waitcnt lgkmcnt(5)
	v_mfma_f32_16x16x32_bf16 v[94:97], v[162:165], v[138:141], v[94:97]
	v_mfma_f32_16x16x32_bf16 v[90:93], v[162:165], v[142:145], v[90:93]
	v_mfma_f32_16x16x32_bf16 v[86:89], v[162:165], v[146:149], v[86:89]
	v_mfma_f32_16x16x32_bf16 v[82:85], v[162:165], v[150:153], v[82:85]
	s_waitcnt lgkmcnt(4)
	v_mfma_f32_16x16x32_bf16 v[78:81], v[166:169], v[138:141], v[78:81]
	v_mfma_f32_16x16x32_bf16 v[74:77], v[166:169], v[142:145], v[74:77]
	v_mfma_f32_16x16x32_bf16 v[70:73], v[166:169], v[146:149], v[70:73]
	v_mfma_f32_16x16x32_bf16 v[66:69], v[166:169], v[150:153], v[66:69]
	s_waitcnt lgkmcnt(3)
	v_mfma_f32_16x16x32_bf16 v[62:65], v[226:229], v[138:141], v[62:65]
	v_mfma_f32_16x16x32_bf16 v[58:61], v[226:229], v[142:145], v[58:61]
	v_mfma_f32_16x16x32_bf16 v[54:57], v[226:229], v[146:149], v[54:57]
	v_mfma_f32_16x16x32_bf16 v[50:53], v[226:229], v[150:153], v[50:53]
	s_waitcnt lgkmcnt(2)
	v_mfma_f32_16x16x32_bf16 v[46:49], v[230:233], v[138:141], v[46:49]
	v_mfma_f32_16x16x32_bf16 v[42:45], v[230:233], v[142:145], v[42:45]
	v_mfma_f32_16x16x32_bf16 v[38:41], v[230:233], v[146:149], v[38:41]
	v_mfma_f32_16x16x32_bf16 v[34:37], v[230:233], v[150:153], v[34:37]
	s_waitcnt lgkmcnt(1)
	v_mfma_f32_16x16x32_bf16 v[30:33], v[234:237], v[138:141], v[30:33]
	v_mfma_f32_16x16x32_bf16 v[26:29], v[234:237], v[142:145], v[26:29]
	v_mfma_f32_16x16x32_bf16 v[22:25], v[234:237], v[146:149], v[22:25]
	v_mfma_f32_16x16x32_bf16 v[18:21], v[234:237], v[150:153], v[18:21]
	s_waitcnt lgkmcnt(0)
	v_mfma_f32_16x16x32_bf16 v[14:17], v[238:241], v[138:141], v[14:17]
	v_mfma_f32_16x16x32_bf16 v[10:13], v[238:241], v[142:145], v[10:13]
	v_mfma_f32_16x16x32_bf16 v[6:9], v[238:241], v[146:149], v[6:9]
	v_mfma_f32_16x16x32_bf16 v[2:5], v[238:241], v[150:153], v[2:5]
	s_cbranch_scc1 .LBB0_292
	v_add_u32_e32 v137, v135, v137
	v_or_b32_e32 v150, 0x10000, v135
	v_or_b32_e32 v154, 0x10400, v135
	v_or_b32_e32 v158, 0x10800, v135
	v_or_b32_e32 v162, 0x10c00, v135
	s_waitcnt vmcnt(6)
	s_barrier
	ds_read_b128 v[130:133], v137 offset:49152
	ds_read_b128 v[138:141], v137 offset:50176
	ds_read_b128 v[142:145], v137 offset:51200
	ds_read_b128 v[146:149], v137 offset:52224
	ds_read_b128 v[150:153], v150
	ds_read_b128 v[154:157], v154
	ds_read_b128 v[158:161], v158
	ds_read_b128 v[162:165], v162
	s_waitcnt lgkmcnt(3)
	v_mfma_f32_16x16x32_bf16 v[126:129], v[150:153], v[130:133], v[126:129]
	v_readlane_b32 s8, v252, 33
	v_readlane_b32 s9, v252, 34
	s_lshl_b32 s7, s7, 8
	v_mfma_f32_16x16x32_bf16 v[122:125], v[150:153], v[138:141], v[122:125]
	v_lshl_or_b32 v182, v1, 3, s7
	v_and_b32_e32 v251, 1, v1
	v_mad_u32_u24 v182, v251, 24, v182
	v_mfma_f32_16x16x32_bf16 v[118:121], v[150:153], v[142:145], v[118:121]
	v_mfma_f32_16x16x32_bf16 v[114:117], v[150:153], v[146:149], v[114:117]
	s_waitcnt lgkmcnt(2)
	v_mfma_f32_16x16x32_bf16 v[110:113], v[154:157], v[130:133], v[110:113]
	v_mfma_f32_16x16x32_bf16 v[106:109], v[154:157], v[138:141], v[106:109]
	v_mfma_f32_16x16x32_bf16 v[102:105], v[154:157], v[142:145], v[102:105]
	v_mfma_f32_16x16x32_bf16 v[98:101], v[154:157], v[146:149], v[98:101]
	s_waitcnt lgkmcnt(1)
	v_mfma_f32_16x16x32_bf16 v[94:97], v[158:161], v[130:133], v[94:97]
	v_mfma_f32_16x16x32_bf16 v[150:153], v[158:161], v[138:141], v[90:93]
	v_mfma_f32_16x16x32_bf16 v[86:89], v[158:161], v[142:145], v[86:89]
	s_nop 1
	v_or_b32_e32 v90, 0x11c00, v135
	ds_read_b128 v[90:93], v90
	v_mfma_f32_16x16x32_bf16 v[154:157], v[158:161], v[146:149], v[82:85]
	s_waitcnt lgkmcnt(1)
	v_mfma_f32_16x16x32_bf16 v[78:81], v[162:165], v[130:133], v[78:81]
	s_nop 0
	v_or_b32_e32 v82, 0x11800, v135
	ds_read_b128 v[82:85], v82
	v_mfma_f32_16x16x32_bf16 v[158:161], v[162:165], v[138:141], v[74:77]
	v_mfma_f32_16x16x32_bf16 v[70:73], v[162:165], v[142:145], v[70:73]
	s_nop 1
	v_or_b32_e32 v74, 0x11400, v135
	ds_read_b128 v[74:77], v74
	v_mfma_f32_16x16x32_bf16 v[162:165], v[162:165], v[146:149], v[66:69]
	s_nop 2
	v_or_b32_e32 v66, 0x11000, v135
	ds_read_b128 v[66:69], v66
	s_waitcnt lgkmcnt(1)
	v_mfma_f32_16x16x32_bf16 v[46:49], v[74:77], v[130:133], v[46:49]
	s_waitcnt vmcnt(0)
	s_waitcnt lgkmcnt(0)
	s_barrier
; DI void st_bf4(u16* p, float a, float b, float c, float d) { *(uint2*)p = make_uint2(pk2(a, b), pk2(c, d)); }
; template <int BM, class Epi>
; DI void gemm_dma(const u16* __restrict__ X, long ldx, const u16* __restrict__ W, long ldw, int K, char* smem,
;                  int m0, int n0, const Epi& epi) {
;     ...
;     bf16x8 xf[MT];
; #pragma unroll
;     for (int i = 0; i < MT; ++i) xf[i] = *(const bf16x8*)(base + (xrow0 + i * 16) * 64 + rd);
; #pragma unroll
;     for (int nh = 0; nh < NT / 4; ++nh) {
;       bf16x8 wf[4];
; #pragma unroll
;       for (int i = 0; i < 4; ++i) wf[i] = *(const bf16x8*)(base + BM * 64 + (wrow0 + (nh * 4 + i) * 16) * 64 + rd);
; #pragma unroll
;       for (int i = 0; i < 4; ++i)
; #pragma unroll
;         for (int mt = 0; mt < MT; ++mt)
;           acc[nh * 4 + i][mt] = __builtin_amdgcn_mfma_f32_16x16x32_bf16(wf[i], xf[mt], acc[nh * 4 + i][mt], 0, 0, 0);
;     }
;   template <int NT, int MT> DI void run(f32x4 (&acc)[NT][MT], int mb, int nb) const {
; #pragma unroll
;     for (int nt = 0; nt < NT; ++nt)
; #pragma unroll
;       for (int mt = 0; mt < MT; ++mt) {
;         f32x4 v = acc[nt][mt];
;         st_bf4(C + (size_t)(mb + mt * 16) * ldc + nb + nt * 16, v[0], v[1], v[2], v[3]);
;       }
;   }
	v_mfma_f32_16x16x32_bf16 v[62:65], v[66:69], v[130:133], v[62:65]
	v_mfma_f32_16x16x32_bf16 v[166:169], v[66:69], v[138:141], v[58:61]
	v_mfma_f32_16x16x32_bf16 v[54:57], v[66:69], v[142:145], v[54:57]
	v_mfma_f32_16x16x32_bf16 v[170:173], v[66:69], v[146:149], v[50:53]
	v_mfma_f32_16x16x32_bf16 v[174:177], v[74:77], v[138:141], v[42:45]
	v_mfma_f32_16x16x32_bf16 v[38:41], v[74:77], v[142:145], v[38:41]
	v_mfma_f32_16x16x32_bf16 v[178:181], v[74:77], v[146:149], v[34:37]
	v_mfma_f32_16x16x32_bf16 v[30:33], v[82:85], v[130:133], v[30:33]
	v_mfma_f32_16x16x32_bf16 v[26:29], v[82:85], v[138:141], v[26:29]
	v_mfma_f32_16x16x32_bf16 v[22:25], v[82:85], v[142:145], v[22:25]
	v_mfma_f32_16x16x32_bf16 v[18:21], v[82:85], v[146:149], v[18:21]
	v_mfma_f32_16x16x32_bf16 v[14:17], v[90:93], v[130:133], v[14:17]
	v_mfma_f32_16x16x32_bf16 v[10:13], v[90:93], v[138:141], v[10:13]
	v_mfma_f32_16x16x32_bf16 v[6:9], v[90:93], v[142:145], v[6:9]
	v_mfma_f32_16x16x32_bf16 v[2:5], v[90:93], v[146:149], v[2:5]
	ds_read_b128 v[130:133], v137
	ds_read_b128 v[138:141], v137 offset:1024
	ds_read_b128 v[142:145], v137 offset:2048
	ds_read_b128 v[146:149], v137 offset:3072
	ds_read_b128 v[34:37], v135 offset:16384
	ds_read_b128 v[42:45], v135 offset:17408
	ds_read_b128 v[50:53], v135 offset:18432
	ds_read_b128 v[186:189], v135 offset:19456
	s_waitcnt lgkmcnt(2)
	v_mfma_f32_16x16x32_bf16 v[110:113], v[42:45], v[130:133], v[110:113]
	v_mfma_f32_16x16x32_bf16 v[106:109], v[42:45], v[138:141], v[106:109]
	v_mfma_f32_16x16x32_bf16 v[102:105], v[42:45], v[142:145], v[102:105]
	s_nop 5
	v_cvt_pk_bf16_f32 v110, v110, v111
	v_cvt_pk_bf16_f32 v111, v112, v113
	v_cvt_pk_bf16_f32 v106, v106, v107
	v_mfma_f32_16x16x32_bf16 v[190:193], v[42:45], v[146:149], v[98:101]
	v_cvt_pk_bf16_f32 v107, v108, v109
	v_cvt_pk_bf16_f32 v102, v102, v103
	v_cvt_pk_bf16_f32 v103, v104, v105
	s_waitcnt lgkmcnt(1)
	v_mfma_f32_16x16x32_bf16 v[82:85], v[50:53], v[138:141], v[150:153]
	v_mfma_f32_16x16x32_bf16 v[66:69], v[50:53], v[146:149], v[154:157]
	s_waitcnt lgkmcnt(0)
	v_mfma_f32_16x16x32_bf16 v[42:45], v[186:189], v[142:145], v[70:73]
	s_nop 2
	ds_read_b128 v[70:73], v135 offset:20480
	ds_read_b128 v[98:101], v135 offset:21504
	ds_read_b128 v[150:153], v135 offset:22528
	ds_read_b128 v[154:157], v135 offset:23552
	v_cvt_pk_bf16_f32 v82, v82, v83
	v_cvt_pk_bf16_f32 v83, v84, v85
	v_mfma_f32_16x16x32_bf16 v[90:93], v[50:53], v[130:133], v[94:97]
	v_cvt_pk_bf16_f32 v66, v66, v67
	v_cvt_pk_bf16_f32 v67, v68, v69
	v_cvt_pk_bf16_f32 v42, v42, v43
	v_mfma_f32_16x16x32_bf16 v[58:61], v[186:189], v[130:133], v[78:81]
	v_cvt_pk_bf16_f32 v43, v44, v45
	s_nop 2
	v_cvt_pk_bf16_f32 v90, v90, v91
	v_cvt_pk_bf16_f32 v91, v92, v93
	s_waitcnt lgkmcnt(3)
	v_mfma_f32_16x16x32_bf16 v[94:97], v[70:73], v[130:133], v[62:65]
	v_mfma_f32_16x16x32_bf16 v[78:81], v[70:73], v[142:145], v[54:57]
	v_cvt_pk_bf16_f32 v58, v58, v59
	v_cvt_pk_bf16_f32 v59, v60, v61
	s_waitcnt lgkmcnt(2)
	v_mfma_f32_16x16x32_bf16 v[62:65], v[98:101], v[130:133], v[46:49]
	v_mfma_f32_16x16x32_bf16 v[54:57], v[98:101], v[138:141], v[174:177]
	v_mfma_f32_16x16x32_bf16 v[46:49], v[98:101], v[142:145], v[38:41]
	v_mfma_f32_16x16x32_bf16 v[38:41], v[98:101], v[146:149], v[178:181]
	v_lshl_add_u32 v98, s38, 8, v136
	v_mfma_f32_16x16x32_bf16 v[126:129], v[34:37], v[130:133], v[126:129]
	s_waitcnt lgkmcnt(1)
	v_mfma_f32_16x16x32_bf16 v[30:33], v[150:153], v[130:133], v[30:33]
	s_waitcnt lgkmcnt(0)
	v_mfma_f32_16x16x32_bf16 v[14:17], v[154:157], v[130:133], v[14:17]
	v_or_b32_e32 v130, v98, v134
	v_ashrrev_i32_e32 v131, 31, v130
	v_lshlrev_b64 v[98:99], 11, v[130:131]
	v_lshl_add_u64 v[98:99], s[8:9], 0, v[98:99]
	v_lshl_add_u64 v[98:99], v[98:99], 0, v[182:183]
	v_cvt_pk_bf16_f32 v100, v126, v127
	v_cvt_pk_bf16_f32 v101, v128, v129
	v_mfma_f32_16x16x32_bf16 v[122:125], v[34:37], v[138:141], v[122:125]
	v_mov_b32_e32 v194, v100
	v_mov_b32_e32 v195, v101
	v_or_b32_e32 v100, 16, v130
	v_ashrrev_i32_e32 v101, 31, v100
	v_lshlrev_b64 v[100:101], 11, v[100:101]
	v_lshl_add_u64 v[100:101], s[8:9], 0, v[100:101]
	v_lshl_add_u64 v[100:101], v[100:101], 0, v[182:183]
	s_nop 1
	v_cvt_pk_bf16_f32 v122, v122, v123
	v_cvt_pk_bf16_f32 v123, v124, v125
	v_mfma_f32_16x16x32_bf16 v[118:121], v[34:37], v[142:145], v[118:121]
	v_mov_b32_e32 v224, v122
	v_mov_b32_e32 v225, v123
	v_or_b32_e32 v122, 32, v130
	v_ashrrev_i32_e32 v123, 31, v122
	v_lshlrev_b64 v[122:123], 11, v[122:123]
	v_lshl_add_u64 v[122:123], s[8:9], 0, v[122:123]
	v_lshl_add_u64 v[122:123], v[122:123], 0, v[182:183]
	s_nop 1
	v_cvt_pk_bf16_f32 v118, v118, v119
	v_cvt_pk_bf16_f32 v119, v120, v121
	v_mfma_f32_16x16x32_bf16 v[114:117], v[34:37], v[146:149], v[114:117]
	v_mov_b32_e32 v228, v118
	v_mov_b32_e32 v229, v119
	v_or_b32_e32 v118, 48, v130
	v_ashrrev_i32_e32 v119, 31, v118
	v_mfma_f32_16x16x32_bf16 v[34:37], v[186:189], v[146:149], v[162:165]
	v_lshlrev_b64 v[118:119], 11, v[118:119]
	v_lshl_add_u64 v[118:119], s[8:9], 0, v[118:119]
	v_lshl_add_u64 v[118:119], v[118:119], 0, v[182:183]
	v_mfma_f32_16x16x32_bf16 v[74:77], v[50:53], v[142:145], v[86:89]
	v_cvt_pk_bf16_f32 v114, v114, v115
	s_nop 2
	v_cvt_pk_bf16_f32 v34, v34, v35
	v_cvt_pk_bf16_f32 v35, v36, v37
	v_mfma_f32_16x16x32_bf16 v[86:89], v[70:73], v[138:141], v[166:169]
	v_mov_b32_e32 v234, v34
	v_mov_b32_e32 v235, v35
	v_cvt_pk_bf16_f32 v34, v94, v95
	v_cvt_pk_bf16_f32 v35, v96, v97
	v_mfma_f32_16x16x32_bf16 v[70:73], v[70:73], v[146:149], v[170:173]
; DI void st_bf4(u16* p, float a, float b, float c, float d) { *(uint2*)p = make_uint2(pk2(a, b), pk2(c, d)); }
;   template <int NT, int MT> DI void run(f32x4 (&acc)[NT][MT], int mb, int nb) const {
; #pragma unroll
;     for (int nt = 0; nt < NT; ++nt)
; #pragma unroll
;       for (int mt = 0; mt < MT; ++mt) {
;         f32x4 v = acc[nt][mt];
;         st_bf4(C + (size_t)(mb + mt * 16) * ldc + nb + nt * 16, v[0], v[1], v[2], v[3]);
;       }
;   }
	v_mov_b32_e32 v236, v34
	v_mov_b32_e32 v237, v35
	s_nop 2
	v_cvt_pk_bf16_f32 v34, v86, v87
	v_cvt_pk_bf16_f32 v35, v88, v89
	v_mov_b32_e32 v240, v34
	v_mov_b32_e32 v241, v35
	v_cvt_pk_bf16_f32 v34, v78, v79
	v_cvt_pk_bf16_f32 v35, v80, v81
	v_mfma_f32_16x16x32_bf16 v[50:53], v[186:189], v[138:141], v[158:161]
	v_mov_b32_e32 v244, v34
	v_mov_b32_e32 v245, v35
	v_cvt_pk_bf16_f32 v34, v70, v71
	v_cvt_pk_bf16_f32 v35, v72, v73
	v_mfma_f32_16x16x32_bf16 v[26:29], v[150:153], v[138:141], v[26:29]
	v_mov_b32_e32 v248, v34
	v_mov_b32_e32 v249, v35
	v_cvt_pk_bf16_f32 v34, v62, v63
	v_cvt_pk_bf16_f32 v35, v64, v65
	v_mfma_f32_16x16x32_bf16 v[22:25], v[150:153], v[142:145], v[22:25]
	v_mov_b32_e32 v238, v34
	v_mov_b32_e32 v239, v35
	s_nop 1
	v_permlane16_swap_b32_e32 v236, v238
	v_permlane16_swap_b32_e32 v237, v239
	global_store_dwordx4 v[98:99], v[236:239], off offset:128
	v_cvt_pk_bf16_f32 v34, v54, v55
	v_cvt_pk_bf16_f32 v35, v56, v57
	v_mfma_f32_16x16x32_bf16 v[18:21], v[150:153], v[146:149], v[18:21]
	v_mov_b32_e32 v242, v34
	v_mov_b32_e32 v243, v35
	s_nop 1
	v_permlane16_swap_b32_e32 v240, v242
	v_permlane16_swap_b32_e32 v241, v243
	global_store_dwordx4 v[100:101], v[240:243], off offset:128
	v_cvt_pk_bf16_f32 v34, v46, v47
	v_cvt_pk_bf16_f32 v35, v48, v49
	v_mfma_f32_16x16x32_bf16 v[10:13], v[154:157], v[138:141], v[10:13]
	v_cvt_pk_bf16_f32 v115, v116, v117
	v_mov_b32_e32 v230, v102
	v_mov_b32_e32 v231, v103
	s_nop 1
	v_permlane16_swap_b32_e32 v228, v230
	v_permlane16_swap_b32_e32 v229, v231
	global_store_dwordx4 v[122:123], v[228:231], off
	v_cvt_pk_bf16_f32 v102, v190, v191
	v_mfma_f32_16x16x32_bf16 v[6:9], v[154:157], v[142:145], v[6:9]
	v_cvt_pk_bf16_f32 v103, v192, v193
	v_cvt_pk_bf16_f32 v74, v74, v75
	v_cvt_pk_bf16_f32 v75, v76, v77
	v_mfma_f32_16x16x32_bf16 v[2:5], v[154:157], v[146:149], v[2:5]
	v_cvt_pk_bf16_f32 v50, v50, v51
	v_cvt_pk_bf16_f32 v51, v52, v53
	v_mov_b32_e32 v246, v34
	v_mov_b32_e32 v247, v35
	s_nop 1
	v_permlane16_swap_b32_e32 v244, v246
	v_permlane16_swap_b32_e32 v245, v247
	global_store_dwordx4 v[122:123], v[244:247], off offset:128
	v_cvt_pk_bf16_f32 v34, v38, v39
	v_cvt_pk_bf16_f32 v35, v40, v41
	v_cvt_pk_bf16_f32 v30, v30, v31
	v_cvt_pk_bf16_f32 v31, v32, v33
	v_cvt_pk_bf16_f32 v26, v26, v27
	v_cvt_pk_bf16_f32 v27, v28, v29
	v_cvt_pk_bf16_f32 v22, v22, v23
	v_cvt_pk_bf16_f32 v23, v24, v25
	v_cvt_pk_bf16_f32 v18, v18, v19
	v_cvt_pk_bf16_f32 v19, v20, v21
	v_cvt_pk_bf16_f32 v14, v14, v15
	v_cvt_pk_bf16_f32 v15, v16, v17
	v_cvt_pk_bf16_f32 v10, v10, v11
	v_cvt_pk_bf16_f32 v11, v12, v13
	v_cvt_pk_bf16_f32 v6, v6, v7
	v_cvt_pk_bf16_f32 v7, v8, v9
	v_cvt_pk_bf16_f32 v2, v2, v3
	v_cvt_pk_bf16_f32 v3, v4, v5
	v_mov_b32_e32 v68, v114
	v_mov_b32_e32 v69, v115
	v_mov_b32_e32 v196, v110
	v_mov_b32_e32 v197, v111
	s_nop 1
	v_permlane16_swap_b32_e32 v194, v196
	v_permlane16_swap_b32_e32 v195, v197
	global_store_dwordx4 v[98:99], v[194:197], off
	v_mov_b32_e32 v226, v106
	v_mov_b32_e32 v227, v107
	s_nop 1
	v_permlane16_swap_b32_e32 v224, v226
	v_permlane16_swap_b32_e32 v225, v227
	global_store_dwordx4 v[100:101], v[224:227], off
	v_mov_b32_e32 v70, v102
	v_mov_b32_e32 v71, v103
	s_nop 1
	v_permlane16_swap_b32_e32 v68, v70
	v_permlane16_swap_b32_e32 v69, v71
	global_store_dwordx4 v[118:119], v[68:71], off
	v_mov_b32_e32 v130, v90
	v_mov_b32_e32 v131, v91
	v_mov_b32_e32 v138, v82
	v_mov_b32_e32 v139, v83
	v_mov_b32_e32 v142, v74
	v_mov_b32_e32 v143, v75
	v_mov_b32_e32 v232, v66
	v_mov_b32_e32 v233, v67
	s_nop 1
	v_permlane16_swap_b32_e32 v232, v234
	v_permlane16_swap_b32_e32 v233, v235
	global_store_dwordx4 v[118:119], v[232:235], off offset:64
	v_mov_b32_e32 v132, v58
	v_mov_b32_e32 v133, v59
	s_nop 1
	v_permlane16_swap_b32_e32 v130, v132
	v_permlane16_swap_b32_e32 v131, v133
	global_store_dwordx4 v[98:99], v[130:133], off offset:64
	v_mov_b32_e32 v140, v50
	v_mov_b32_e32 v141, v51
	s_nop 1
	v_permlane16_swap_b32_e32 v138, v140
	v_permlane16_swap_b32_e32 v139, v141
	global_store_dwordx4 v[100:101], v[138:141], off offset:64
	v_mov_b32_e32 v144, v42
	v_mov_b32_e32 v145, v43
	s_nop 1
	v_permlane16_swap_b32_e32 v142, v144
	v_permlane16_swap_b32_e32 v143, v145
	global_store_dwordx4 v[122:123], v[142:145], off offset:64
	v_mov_b32_e32 v250, v34
	v_mov_b32_e32 v251, v35
	s_nop 1
	v_permlane16_swap_b32_e32 v248, v250
	v_permlane16_swap_b32_e32 v249, v251
	global_store_dwordx4 v[118:119], v[248:251], off offset:128
	v_mov_b32_e32 v68, v30
	v_mov_b32_e32 v69, v31
	v_mov_b32_e32 v130, v26
	v_mov_b32_e32 v131, v27
	v_mov_b32_e32 v138, v22
	v_mov_b32_e32 v139, v23
	v_mov_b32_e32 v142, v18
	v_mov_b32_e32 v143, v19
	v_mov_b32_e32 v70, v14
	v_mov_b32_e32 v71, v15
	s_nop 1
	v_permlane16_swap_b32_e32 v68, v70
	v_permlane16_swap_b32_e32 v69, v71
	global_store_dwordx4 v[98:99], v[68:71], off offset:192
	v_mov_b32_e32 v132, v10
	v_mov_b32_e32 v133, v11
	s_nop 1
	v_permlane16_swap_b32_e32 v130, v132
	v_permlane16_swap_b32_e32 v131, v133
	global_store_dwordx4 v[100:101], v[130:133], off offset:192
	v_mov_b32_e32 v140, v6
	v_mov_b32_e32 v141, v7
	s_nop 1
	v_permlane16_swap_b32_e32 v138, v140
	v_permlane16_swap_b32_e32 v139, v141
	global_store_dwordx4 v[122:123], v[138:141], off offset:192
	v_mov_b32_e32 v144, v2
	v_mov_b32_e32 v145, v3
	s_nop 1
	v_permlane16_swap_b32_e32 v142, v144
	v_permlane16_swap_b32_e32 v143, v145
	global_store_dwordx4 v[118:119], v[142:145], off offset:192
	s_branch .LBB0_285

; template <int N> DI void wait_vm() { asm volatile("s_waitcnt vmcnt(%0)" ::"n"(N) : "memory"); }
; template <int BM, class Epi>
; DI void gemm_dma(const u16* __restrict__ X, long ldx, const u16* __restrict__ W, long ldw, int K, char* smem,
;                  int m0, int n0, const Epi& epi) {
;     ...
;   do {
;     if (kt + D - 2 < nk) wait_vm<PW * (D - 2)>(); else wait_vm<0>();
;     __syncthreads();
;     if (kt + D - 1 < nk) GD_ISSUE(nxt)
;     nxt = (nxt + 1 == D) ? 0 : nxt + 1;
;     const char* base = smem + cur * STG;
;     cur = (cur + 1 == D) ? 0 : cur + 1;
;     bf16x8 xf[MT];
; #pragma unroll
;     for (int i = 0; i < MT; ++i) xf[i] = *(const bf16x8*)(base + (xrow0 + i * 16) * 64 + rd);
; #pragma unroll
;     for (int nh = 0; nh < NT / 4; ++nh) {
;       bf16x8 wf[4];
; #pragma unroll
;       for (int i = 0; i < 4; ++i) wf[i] = *(const bf16x8*)(base + BM * 64 + (wrow0 + (nh * 4 + i) * 16) * 64 + rd);
; #pragma unroll
;       for (int i = 0; i < 4; ++i)
; #pragma unroll
;         for (int mt = 0; mt < MT; ++mt)
;           acc[nh * 4 + i][mt] = __builtin_amdgcn_mfma_f32_16x16x32_bf16(wf[i], xf[mt], acc[nh * 4 + i][mt], 0, 0, 0);
;     }
;   } while (++kt < nk);
;     ...
;   epi.run(acc, m0 + xrow0 + lr, n0 + wrow0 + 4 * g);
.LBB0_1139:
	s_mul_i32 s12, s10, 0x6000
	v_lshl_add_u64 v[196:197], v[130:131], 0, s[42:43]
	s_waitcnt vmcnt(6)
	s_barrier
	s_mul_i32 s98, s11, 0x6000
	v_or_b32_e32 v137, s98, v134
	v_add_u32_e32 v150, v137, v136
	ds_read_b128 v[138:141], v150
	ds_read_b128 v[142:145], v150 offset:1024
	ds_read_b128 v[146:149], v150 offset:2048
	ds_read_b128 v[150:153], v150 offset:3072
	ds_read_b128 v[154:157], v137 offset:16384
	ds_read_b128 v[158:161], v137 offset:17408
	ds_read_b128 v[162:165], v137 offset:18432
	ds_read_b128 v[166:169], v137 offset:19456
	ds_read_b128 v[226:229], v137 offset:20480
	ds_read_b128 v[230:233], v137 offset:21504
	ds_read_b128 v[234:237], v137 offset:22528
	ds_read_b128 v[238:241], v137 offset:23552
	s_add_i32 s13, s12, s8
	s_mov_b32 m0, s13
	s_nop 0
	global_load_lds_dwordx4 v[196:197], off
	v_lshl_add_u64 v[224:225], v[196:197], 0, s[58:59]
	s_add_i32 s14, s13, 0x400
	s_mov_b32 m0, s14
	s_nop 0
	global_load_lds_dwordx4 v[224:225], off
	v_lshl_add_u64 v[224:225], v[196:197], 0, s[16:17]
	s_add_i32 s14, s13, 0x800
	s_mov_b32 m0, s14
	s_nop 0
	global_load_lds_dwordx4 v[224:225], off
	v_lshl_add_u64 v[196:197], v[196:197], 0, s[18:19]
	s_addk_i32 s13, 0xc00
	s_mov_b32 m0, s13
	s_nop 0
	global_load_lds_dwordx4 v[196:197], off
	s_add_i32 s12, s12, s9
	v_lshl_add_u64 v[194:195], v[128:129], 0, s[42:43]
	s_mov_b32 m0, s12
	s_nop 0
	global_load_lds_dwordx4 v[194:195], off
	s_addk_i32 s12, 0x400
	v_lshl_add_u64 v[194:195], v[194:195], 0, s[58:59]
	s_mov_b32 m0, s12
	s_nop 0
	global_load_lds_dwordx4 v[194:195], off
	s_waitcnt lgkmcnt(7)
	v_mfma_f32_16x16x32_bf16 v[124:127], v[154:157], v[138:141], v[124:127]
	s_add_i32 s10, s10, 1
	s_add_i32 s11, s11, 1
	s_cmp_lg_u32 s10, 3
	v_mfma_f32_16x16x32_bf16 v[120:123], v[154:157], v[142:145], v[120:123]
	s_cselect_b32 s10, s10, 0
	s_cmp_lg_u32 s11, 3
	s_cselect_b32 s11, s11, 0
	v_mfma_f32_16x16x32_bf16 v[116:119], v[154:157], v[146:149], v[116:119]
	s_add_u32 s42, s42, 64
	s_addc_u32 s43, s43, 0
	s_cmpk_lg_i32 s42, 0xf80
	v_mfma_f32_16x16x32_bf16 v[112:115], v[154:157], v[150:153], v[112:115]
	s_waitcnt lgkmcnt(6)
	v_mfma_f32_16x16x32_bf16 v[108:111], v[158:161], v[138:141], v[108:111]
	v_mfma_f32_16x16x32_bf16 v[104:107], v[158:161], v[142:145], v[104:107]
	v_mfma_f32_16x16x32_bf16 v[100:103], v[158:161], v[146:149], v[100:103]
	v_mfma_f32_16x16x32_bf16 v[96:99], v[158:161], v[150:153], v[96:99]
	s_waitcnt lgkmcnt(5)
	v_mfma_f32_16x16x32_bf16 v[92:95], v[162:165], v[138:141], v[92:95]
	v_mfma_f32_16x16x32_bf16 v[88:91], v[162:165], v[142:145], v[88:91]
	v_mfma_f32_16x16x32_bf16 v[84:87], v[162:165], v[146:149], v[84:87]
	v_mfma_f32_16x16x32_bf16 v[80:83], v[162:165], v[150:153], v[80:83]
	s_waitcnt lgkmcnt(4)
	v_mfma_f32_16x16x32_bf16 v[76:79], v[166:169], v[138:141], v[76:79]
	v_mfma_f32_16x16x32_bf16 v[72:75], v[166:169], v[142:145], v[72:75]
	v_mfma_f32_16x16x32_bf16 v[68:71], v[166:169], v[146:149], v[68:71]
	v_mfma_f32_16x16x32_bf16 v[64:67], v[166:169], v[150:153], v[64:67]
	s_waitcnt lgkmcnt(3)
	v_mfma_f32_16x16x32_bf16 v[60:63], v[226:229], v[138:141], v[60:63]
	v_mfma_f32_16x16x32_bf16 v[56:59], v[226:229], v[142:145], v[56:59]
	v_mfma_f32_16x16x32_bf16 v[52:55], v[226:229], v[146:149], v[52:55]
	v_mfma_f32_16x16x32_bf16 v[48:51], v[226:229], v[150:153], v[48:51]
	s_waitcnt lgkmcnt(2)
	v_mfma_f32_16x16x32_bf16 v[44:47], v[230:233], v[138:141], v[44:47]
	v_mfma_f32_16x16x32_bf16 v[40:43], v[230:233], v[142:145], v[40:43]
	v_mfma_f32_16x16x32_bf16 v[36:39], v[230:233], v[146:149], v[36:39]
	v_mfma_f32_16x16x32_bf16 v[32:35], v[230:233], v[150:153], v[32:35]
	s_waitcnt lgkmcnt(1)
	v_mfma_f32_16x16x32_bf16 v[28:31], v[234:237], v[138:141], v[28:31]
	v_mfma_f32_16x16x32_bf16 v[24:27], v[234:237], v[142:145], v[24:27]
	v_mfma_f32_16x16x32_bf16 v[20:23], v[234:237], v[146:149], v[20:23]
	v_mfma_f32_16x16x32_bf16 v[16:19], v[234:237], v[150:153], v[16:19]
	s_waitcnt lgkmcnt(0)
	v_mfma_f32_16x16x32_bf16 v[12:15], v[238:241], v[138:141], v[12:15]
	v_mfma_f32_16x16x32_bf16 v[8:11], v[238:241], v[142:145], v[8:11]
	v_mfma_f32_16x16x32_bf16 v[4:7], v[238:241], v[146:149], v[4:7]
	v_mfma_f32_16x16x32_bf16 v[0:3], v[238:241], v[150:153], v[0:3]
	s_cbranch_scc1 .LBB0_1139
	v_add_u32_e32 v180, v134, v136
	v_or_b32_e32 v148, 0x10000, v134
	v_or_b32_e32 v152, 0x10400, v134
	v_or_b32_e32 v156, 0x10800, v134
	v_or_b32_e32 v160, 0x10c00, v134
	s_waitcnt vmcnt(6)
	s_barrier
	ds_read_b128 v[128:131], v180 offset:49152
	ds_read_b128 v[136:139], v180 offset:50176
	ds_read_b128 v[140:143], v180 offset:51200
	ds_read_b128 v[144:147], v180 offset:52224
	ds_read_b128 v[148:151], v148
	ds_read_b128 v[152:155], v152
	ds_read_b128 v[156:159], v156
	ds_read_b128 v[160:163], v160
	s_waitcnt lgkmcnt(3)
	v_mfma_f32_16x16x32_bf16 v[124:127], v[148:151], v[128:131], v[124:127]
	v_readlane_b32 s8, v252, 33
	v_readlane_b32 s9, v252, 34
	s_lshl_b32 s7, s7, 8
	v_mfma_f32_16x16x32_bf16 v[120:123], v[148:151], v[136:139], v[120:123]
	v_lshl_or_b32 v182, v132, 3, s7
	v_and_b32_e32 v251, 1, v132
	v_mad_u32_u24 v182, v251, 24, v182
	v_mfma_f32_16x16x32_bf16 v[116:119], v[148:151], v[140:143], v[116:119]
	v_mfma_f32_16x16x32_bf16 v[112:115], v[148:151], v[144:147], v[112:115]
	s_waitcnt lgkmcnt(2)
	v_mfma_f32_16x16x32_bf16 v[108:111], v[152:155], v[128:131], v[108:111]
	v_mfma_f32_16x16x32_bf16 v[104:107], v[152:155], v[136:139], v[104:107]
	v_mfma_f32_16x16x32_bf16 v[100:103], v[152:155], v[140:143], v[100:103]
	v_mfma_f32_16x16x32_bf16 v[96:99], v[152:155], v[144:147], v[96:99]
	s_waitcnt lgkmcnt(1)
	v_mfma_f32_16x16x32_bf16 v[92:95], v[156:159], v[128:131], v[92:95]
	v_mfma_f32_16x16x32_bf16 v[148:151], v[156:159], v[136:139], v[88:91]
	v_mfma_f32_16x16x32_bf16 v[84:87], v[156:159], v[140:143], v[84:87]
	s_nop 1
	v_or_b32_e32 v88, 0x11c00, v134
	ds_read_b128 v[88:91], v88
	v_mfma_f32_16x16x32_bf16 v[152:155], v[156:159], v[144:147], v[80:83]
	s_waitcnt lgkmcnt(1)
	v_mfma_f32_16x16x32_bf16 v[76:79], v[160:163], v[128:131], v[76:79]
	s_nop 0
	v_or_b32_e32 v80, 0x11800, v134
	ds_read_b128 v[80:83], v80
	v_mfma_f32_16x16x32_bf16 v[156:159], v[160:163], v[136:139], v[72:75]
	v_mfma_f32_16x16x32_bf16 v[68:71], v[160:163], v[140:143], v[68:71]
	s_nop 1
	v_or_b32_e32 v72, 0x11400, v134
	ds_read_b128 v[72:75], v72
	v_mfma_f32_16x16x32_bf16 v[160:163], v[160:163], v[144:147], v[64:67]
	s_nop 2
	v_or_b32_e32 v64, 0x11000, v134
	ds_read_b128 v[64:67], v64
	s_waitcnt lgkmcnt(1)
	v_mfma_f32_16x16x32_bf16 v[44:47], v[72:75], v[128:131], v[44:47]
	s_waitcnt vmcnt(0)
	s_waitcnt lgkmcnt(0)
	s_barrier
; DI void st_bf4(u16* p, float a, float b, float c, float d) { *(uint2*)p = make_uint2(pk2(a, b), pk2(c, d)); }
; template <int BM, class Epi>
; DI void gemm_dma(const u16* __restrict__ X, long ldx, const u16* __restrict__ W, long ldw, int K, char* smem,
;                  int m0, int n0, const Epi& epi) {
;     ...
;     bf16x8 xf[MT];
; #pragma unroll
;     for (int i = 0; i < MT; ++i) xf[i] = *(const bf16x8*)(base + (xrow0 + i * 16) * 64 + rd);
; #pragma unroll
;     for (int nh = 0; nh < NT / 4; ++nh) {
;       bf16x8 wf[4];
; #pragma unroll
;       for (int i = 0; i < 4; ++i) wf[i] = *(const bf16x8*)(base + BM * 64 + (wrow0 + (nh * 4 + i) * 16) * 64 + rd);
; #pragma unroll
;       for (int i = 0; i < 4; ++i)
; #pragma unroll
;         for (int mt = 0; mt < MT; ++mt)
;           acc[nh * 4 + i][mt] = __builtin_amdgcn_mfma_f32_16x16x32_bf16(wf[i], xf[mt], acc[nh * 4 + i][mt], 0, 0, 0);
;     }
;   template <int NT, int MT> DI void run(f32x4 (&acc)[NT][MT], int mb, int nb) const {
; #pragma unroll
;     for (int nt = 0; nt < NT; ++nt)
; #pragma unroll
;       for (int mt = 0; mt < MT; ++mt) {
;         f32x4 v = acc[nt][mt];
;         st_bf4(C + (size_t)(mb + mt * 16) * ldc + nb + nt * 16, v[0], v[1], v[2], v[3]);
;       }
;   }
	v_mfma_f32_16x16x32_bf16 v[60:63], v[64:67], v[128:131], v[60:63]
	v_mfma_f32_16x16x32_bf16 v[164:167], v[64:67], v[136:139], v[56:59]
	v_mfma_f32_16x16x32_bf16 v[52:55], v[64:67], v[140:143], v[52:55]
	v_mfma_f32_16x16x32_bf16 v[168:171], v[64:67], v[144:147], v[48:51]
	v_mfma_f32_16x16x32_bf16 v[172:175], v[72:75], v[136:139], v[40:43]
	v_mfma_f32_16x16x32_bf16 v[36:39], v[72:75], v[140:143], v[36:39]
	v_mfma_f32_16x16x32_bf16 v[176:179], v[72:75], v[144:147], v[32:35]
	v_mfma_f32_16x16x32_bf16 v[28:31], v[80:83], v[128:131], v[28:31]
	v_mfma_f32_16x16x32_bf16 v[24:27], v[80:83], v[136:139], v[24:27]
	v_mfma_f32_16x16x32_bf16 v[20:23], v[80:83], v[140:143], v[20:23]
	v_mfma_f32_16x16x32_bf16 v[16:19], v[80:83], v[144:147], v[16:19]
	v_mfma_f32_16x16x32_bf16 v[12:15], v[88:91], v[128:131], v[12:15]
	v_mfma_f32_16x16x32_bf16 v[8:11], v[88:91], v[136:139], v[8:11]
	v_mfma_f32_16x16x32_bf16 v[4:7], v[88:91], v[140:143], v[4:7]
	v_mfma_f32_16x16x32_bf16 v[0:3], v[88:91], v[144:147], v[0:3]
	ds_read_b128 v[128:131], v180
	ds_read_b128 v[136:139], v180 offset:1024
	ds_read_b128 v[140:143], v180 offset:2048
	ds_read_b128 v[144:147], v180 offset:3072
	ds_read_b128 v[32:35], v134 offset:16384
	ds_read_b128 v[40:43], v134 offset:17408
	ds_read_b128 v[48:51], v134 offset:18432
	ds_read_b128 v[186:189], v134 offset:19456
	s_waitcnt lgkmcnt(2)
	v_mfma_f32_16x16x32_bf16 v[108:111], v[40:43], v[128:131], v[108:111]
	v_mfma_f32_16x16x32_bf16 v[104:107], v[40:43], v[136:139], v[104:107]
	v_mfma_f32_16x16x32_bf16 v[100:103], v[40:43], v[140:143], v[100:103]
	s_nop 5
	v_cvt_pk_bf16_f32 v108, v108, v109
	v_cvt_pk_bf16_f32 v109, v110, v111
	v_cvt_pk_bf16_f32 v104, v104, v105
	v_mfma_f32_16x16x32_bf16 v[190:193], v[40:43], v[144:147], v[96:99]
	v_cvt_pk_bf16_f32 v105, v106, v107
	v_cvt_pk_bf16_f32 v100, v100, v101
	v_cvt_pk_bf16_f32 v101, v102, v103
	s_waitcnt lgkmcnt(1)
	v_mfma_f32_16x16x32_bf16 v[80:83], v[48:51], v[136:139], v[148:151]
	v_mfma_f32_16x16x32_bf16 v[64:67], v[48:51], v[144:147], v[152:155]
	s_waitcnt lgkmcnt(0)
	v_mfma_f32_16x16x32_bf16 v[40:43], v[186:189], v[140:143], v[68:71]
	s_nop 2
	ds_read_b128 v[68:71], v134 offset:20480
	ds_read_b128 v[96:99], v134 offset:21504
	ds_read_b128 v[148:151], v134 offset:22528
	ds_read_b128 v[152:155], v134 offset:23552
	v_cvt_pk_bf16_f32 v80, v80, v81
	v_cvt_pk_bf16_f32 v81, v82, v83
	v_mfma_f32_16x16x32_bf16 v[88:91], v[48:51], v[128:131], v[92:95]
	v_cvt_pk_bf16_f32 v64, v64, v65
	v_cvt_pk_bf16_f32 v65, v66, v67
	v_cvt_pk_bf16_f32 v40, v40, v41
	v_mfma_f32_16x16x32_bf16 v[56:59], v[186:189], v[128:131], v[76:79]
	v_cvt_pk_bf16_f32 v41, v42, v43
	s_nop 2
	v_cvt_pk_bf16_f32 v88, v88, v89
	v_cvt_pk_bf16_f32 v89, v90, v91
	s_waitcnt lgkmcnt(3)
	v_mfma_f32_16x16x32_bf16 v[92:95], v[68:71], v[128:131], v[60:63]
	v_mfma_f32_16x16x32_bf16 v[76:79], v[68:71], v[140:143], v[52:55]
	v_cvt_pk_bf16_f32 v56, v56, v57
	v_cvt_pk_bf16_f32 v57, v58, v59
	s_waitcnt lgkmcnt(2)
	v_mfma_f32_16x16x32_bf16 v[60:63], v[96:99], v[128:131], v[44:47]
	v_mfma_f32_16x16x32_bf16 v[52:55], v[96:99], v[136:139], v[172:175]
	v_mfma_f32_16x16x32_bf16 v[44:47], v[96:99], v[140:143], v[36:39]
	v_mfma_f32_16x16x32_bf16 v[36:39], v[96:99], v[144:147], v[176:179]
	v_lshl_add_u32 v96, s40, 8, v135
	v_mfma_f32_16x16x32_bf16 v[124:127], v[32:35], v[128:131], v[124:127]
	s_waitcnt lgkmcnt(1)
	v_mfma_f32_16x16x32_bf16 v[28:31], v[148:151], v[128:131], v[28:31]
	s_waitcnt lgkmcnt(0)
	v_mfma_f32_16x16x32_bf16 v[12:15], v[152:155], v[128:131], v[12:15]
	v_or_b32_e32 v128, v96, v133
	v_ashrrev_i32_e32 v129, 31, v128
	v_lshlrev_b64 v[96:97], 11, v[128:129]
	v_lshl_add_u64 v[96:97], s[8:9], 0, v[96:97]
	v_lshl_add_u64 v[96:97], v[96:97], 0, v[182:183]
	v_cvt_pk_bf16_f32 v98, v124, v125
	v_cvt_pk_bf16_f32 v99, v126, v127
	v_mfma_f32_16x16x32_bf16 v[120:123], v[32:35], v[136:139], v[120:123]
	v_mov_b32_e32 v194, v98
	v_mov_b32_e32 v195, v99
	v_or_b32_e32 v98, 16, v128
	v_ashrrev_i32_e32 v99, 31, v98
	v_lshlrev_b64 v[98:99], 11, v[98:99]
	v_lshl_add_u64 v[98:99], s[8:9], 0, v[98:99]
	v_lshl_add_u64 v[98:99], v[98:99], 0, v[182:183]
	s_nop 1
	v_cvt_pk_bf16_f32 v120, v120, v121
	v_cvt_pk_bf16_f32 v121, v122, v123
	v_mfma_f32_16x16x32_bf16 v[116:119], v[32:35], v[140:143], v[116:119]
	v_mov_b32_e32 v224, v120
	v_mov_b32_e32 v225, v121
	v_or_b32_e32 v120, 32, v128
	v_ashrrev_i32_e32 v121, 31, v120
	v_lshlrev_b64 v[120:121], 11, v[120:121]
	v_lshl_add_u64 v[120:121], s[8:9], 0, v[120:121]
	v_lshl_add_u64 v[120:121], v[120:121], 0, v[182:183]
	s_nop 1
	v_cvt_pk_bf16_f32 v116, v116, v117
	v_cvt_pk_bf16_f32 v117, v118, v119
	v_mfma_f32_16x16x32_bf16 v[112:115], v[32:35], v[144:147], v[112:115]
	v_mov_b32_e32 v228, v116
	v_mov_b32_e32 v229, v117
	v_or_b32_e32 v116, 48, v128
	v_ashrrev_i32_e32 v117, 31, v116
	v_mfma_f32_16x16x32_bf16 v[32:35], v[186:189], v[144:147], v[160:163]
	v_lshlrev_b64 v[116:117], 11, v[116:117]
	v_lshl_add_u64 v[116:117], s[8:9], 0, v[116:117]
	v_lshl_add_u64 v[116:117], v[116:117], 0, v[182:183]
	v_mfma_f32_16x16x32_bf16 v[72:75], v[48:51], v[140:143], v[84:87]
	v_cvt_pk_bf16_f32 v112, v112, v113
	s_nop 2
	v_cvt_pk_bf16_f32 v32, v32, v33
	v_cvt_pk_bf16_f32 v33, v34, v35
	v_mfma_f32_16x16x32_bf16 v[84:87], v[68:71], v[136:139], v[164:167]
	v_mov_b32_e32 v234, v32
	v_mov_b32_e32 v235, v33
	v_cvt_pk_bf16_f32 v32, v92, v93
	v_cvt_pk_bf16_f32 v33, v94, v95
	v_mfma_f32_16x16x32_bf16 v[68:71], v[68:71], v[144:147], v[168:171]
; DI void st_bf4(u16* p, float a, float b, float c, float d) { *(uint2*)p = make_uint2(pk2(a, b), pk2(c, d)); }
;   template <int NT, int MT> DI void run(f32x4 (&acc)[NT][MT], int mb, int nb) const {
; #pragma unroll
;     for (int nt = 0; nt < NT; ++nt)
; #pragma unroll
;       for (int mt = 0; mt < MT; ++mt) {
;         f32x4 v = acc[nt][mt];
;         st_bf4(C + (size_t)(mb + mt * 16) * ldc + nb + nt * 16, v[0], v[1], v[2], v[3]);
;       }
;   }
	v_mov_b32_e32 v236, v32
	v_mov_b32_e32 v237, v33
	s_nop 2
	v_cvt_pk_bf16_f32 v32, v84, v85
	v_cvt_pk_bf16_f32 v33, v86, v87
	v_mov_b32_e32 v240, v32
	v_mov_b32_e32 v241, v33
	v_cvt_pk_bf16_f32 v32, v76, v77
	v_cvt_pk_bf16_f32 v33, v78, v79
	v_mfma_f32_16x16x32_bf16 v[48:51], v[186:189], v[136:139], v[156:159]
	v_mov_b32_e32 v244, v32
	v_mov_b32_e32 v245, v33
	v_cvt_pk_bf16_f32 v32, v68, v69
	v_cvt_pk_bf16_f32 v33, v70, v71
	v_mfma_f32_16x16x32_bf16 v[24:27], v[148:151], v[136:139], v[24:27]
	v_mov_b32_e32 v248, v32
	v_mov_b32_e32 v249, v33
	v_cvt_pk_bf16_f32 v32, v60, v61
	v_cvt_pk_bf16_f32 v33, v62, v63
	v_mfma_f32_16x16x32_bf16 v[20:23], v[148:151], v[140:143], v[20:23]
	v_mov_b32_e32 v238, v32
	v_mov_b32_e32 v239, v33
	s_nop 1
	v_permlane16_swap_b32_e32 v236, v238
	v_permlane16_swap_b32_e32 v237, v239
	global_store_dwordx4 v[96:97], v[236:239], off offset:128
	v_cvt_pk_bf16_f32 v32, v52, v53
	v_cvt_pk_bf16_f32 v33, v54, v55
	v_mfma_f32_16x16x32_bf16 v[16:19], v[148:151], v[144:147], v[16:19]
	v_mov_b32_e32 v242, v32
	v_mov_b32_e32 v243, v33
	s_nop 1
	v_permlane16_swap_b32_e32 v240, v242
	v_permlane16_swap_b32_e32 v241, v243
	global_store_dwordx4 v[98:99], v[240:243], off offset:128
	v_cvt_pk_bf16_f32 v32, v44, v45
	v_cvt_pk_bf16_f32 v33, v46, v47
	v_mfma_f32_16x16x32_bf16 v[8:11], v[152:155], v[136:139], v[8:11]
	v_cvt_pk_bf16_f32 v113, v114, v115
	v_mov_b32_e32 v230, v100
	v_mov_b32_e32 v231, v101
	s_nop 1
	v_permlane16_swap_b32_e32 v228, v230
	v_permlane16_swap_b32_e32 v229, v231
	global_store_dwordx4 v[120:121], v[228:231], off
	v_cvt_pk_bf16_f32 v100, v190, v191
	v_mfma_f32_16x16x32_bf16 v[4:7], v[152:155], v[140:143], v[4:7]
	v_cvt_pk_bf16_f32 v101, v192, v193
	v_cvt_pk_bf16_f32 v72, v72, v73
	v_cvt_pk_bf16_f32 v73, v74, v75
	v_mfma_f32_16x16x32_bf16 v[0:3], v[152:155], v[144:147], v[0:3]
	v_cvt_pk_bf16_f32 v48, v48, v49
	v_cvt_pk_bf16_f32 v49, v50, v51
	v_mov_b32_e32 v246, v32
	v_mov_b32_e32 v247, v33
	s_nop 1
	v_permlane16_swap_b32_e32 v244, v246
	v_permlane16_swap_b32_e32 v245, v247
	global_store_dwordx4 v[120:121], v[244:247], off offset:128
	v_cvt_pk_bf16_f32 v32, v36, v37
	v_cvt_pk_bf16_f32 v33, v38, v39
	v_cvt_pk_bf16_f32 v28, v28, v29
	v_cvt_pk_bf16_f32 v29, v30, v31
	v_cvt_pk_bf16_f32 v24, v24, v25
	v_cvt_pk_bf16_f32 v25, v26, v27
	v_cvt_pk_bf16_f32 v20, v20, v21
	v_cvt_pk_bf16_f32 v21, v22, v23
	v_cvt_pk_bf16_f32 v16, v16, v17
	v_cvt_pk_bf16_f32 v17, v18, v19
	v_cvt_pk_bf16_f32 v12, v12, v13
	v_cvt_pk_bf16_f32 v13, v14, v15
	v_cvt_pk_bf16_f32 v8, v8, v9
	v_cvt_pk_bf16_f32 v9, v10, v11
	v_cvt_pk_bf16_f32 v4, v4, v5
	v_cvt_pk_bf16_f32 v5, v6, v7
	v_cvt_pk_bf16_f32 v0, v0, v1
	v_cvt_pk_bf16_f32 v1, v2, v3
	v_mov_b32_e32 v66, v112
	v_mov_b32_e32 v67, v113
	v_mov_b32_e32 v196, v108
	v_mov_b32_e32 v197, v109
	s_nop 1
	v_permlane16_swap_b32_e32 v194, v196
	v_permlane16_swap_b32_e32 v195, v197
	global_store_dwordx4 v[96:97], v[194:197], off
	v_mov_b32_e32 v226, v104
	v_mov_b32_e32 v227, v105
	s_nop 1
	v_permlane16_swap_b32_e32 v224, v226
	v_permlane16_swap_b32_e32 v225, v227
	global_store_dwordx4 v[98:99], v[224:227], off
	v_mov_b32_e32 v68, v100
	v_mov_b32_e32 v69, v101
	s_nop 1
	v_permlane16_swap_b32_e32 v66, v68
	v_permlane16_swap_b32_e32 v67, v69
	global_store_dwordx4 v[116:117], v[66:69], off
	v_mov_b32_e32 v128, v88
	v_mov_b32_e32 v129, v89
	v_mov_b32_e32 v136, v80
	v_mov_b32_e32 v137, v81
	v_mov_b32_e32 v140, v72
	v_mov_b32_e32 v141, v73
	v_mov_b32_e32 v232, v64
	v_mov_b32_e32 v233, v65
	s_nop 1
	v_permlane16_swap_b32_e32 v232, v234
	v_permlane16_swap_b32_e32 v233, v235
	global_store_dwordx4 v[116:117], v[232:235], off offset:64
	v_mov_b32_e32 v130, v56
	v_mov_b32_e32 v131, v57
	s_nop 1
	v_permlane16_swap_b32_e32 v128, v130
	v_permlane16_swap_b32_e32 v129, v131
	global_store_dwordx4 v[96:97], v[128:131], off offset:64
	v_mov_b32_e32 v138, v48
	v_mov_b32_e32 v139, v49
	s_nop 1
	v_permlane16_swap_b32_e32 v136, v138
	v_permlane16_swap_b32_e32 v137, v139
	global_store_dwordx4 v[98:99], v[136:139], off offset:64
	v_mov_b32_e32 v142, v40
	v_mov_b32_e32 v143, v41
	s_nop 1
	v_permlane16_swap_b32_e32 v140, v142
	v_permlane16_swap_b32_e32 v141, v143
	global_store_dwordx4 v[120:121], v[140:143], off offset:64
	v_mov_b32_e32 v250, v32
	v_mov_b32_e32 v251, v33
	s_nop 1
	v_permlane16_swap_b32_e32 v248, v250
	v_permlane16_swap_b32_e32 v249, v251
	global_store_dwordx4 v[116:117], v[248:251], off offset:128
	v_mov_b32_e32 v66, v28
	v_mov_b32_e32 v67, v29
	v_mov_b32_e32 v128, v24
	v_mov_b32_e32 v129, v25
	v_mov_b32_e32 v136, v20
	v_mov_b32_e32 v137, v21
	v_mov_b32_e32 v140, v16
	v_mov_b32_e32 v141, v17
	v_mov_b32_e32 v68, v12
	v_mov_b32_e32 v69, v13
	s_nop 1
	v_permlane16_swap_b32_e32 v66, v68
	v_permlane16_swap_b32_e32 v67, v69
	global_store_dwordx4 v[96:97], v[66:69], off offset:192
	v_mov_b32_e32 v130, v8
	v_mov_b32_e32 v131, v9
	s_nop 1
	v_permlane16_swap_b32_e32 v128, v130
	v_permlane16_swap_b32_e32 v129, v131
	global_store_dwordx4 v[98:99], v[128:131], off offset:192
	v_mov_b32_e32 v138, v4
	v_mov_b32_e32 v139, v5
	s_nop 1
	v_permlane16_swap_b32_e32 v136, v138
	v_permlane16_swap_b32_e32 v137, v139
	global_store_dwordx4 v[120:121], v[136:139], off offset:192
	v_mov_b32_e32 v142, v0
	v_mov_b32_e32 v143, v1
	s_nop 1
	v_permlane16_swap_b32_e32 v140, v142
	v_permlane16_swap_b32_e32 v141, v143
	global_store_dwordx4 v[116:117], v[140:143], off offset:192
	s_branch .LBB0_1132
